# prep norm loop: L2 warm-up touch of the wave's next item rows; lists-phase prefix with 32 loads in flight per chunk (on top of the gating readlane rewrite and norm-load hoist)
# speedup vs baseline: 1.0040x; 1.0040x over previous
; __device__ __forceinline__ float bflo(unsigned w) { return __uint_as_float(w << 16); }
; __device__ __forceinline__ float bfhi(unsigned w) { return __uint_as_float(w & 0xffff0000u); }
; __device__ __forceinline__ void prep_phase(const Args& a, LAS unsigned char* lds, int tid, int lane, int wave) {
;     ...
;     for (int wv = BID * NWAVES + wave; wv < Bn * 8 * (S / 64); wv += nwv) {
;         const int bh = wv / (S / 64), t = (wv % (S / 64)) * 64 + lane; const int b = bh >> 3, h = 8 + (bh & 7);
;         const v4u* qp = (const v4u*)(Q + ((size_t)(b * S + t)) * D + h * 64); const v4u* kp = (const v4u*)(Q + (size_t)32 * MiB + ((size_t)(b * S + t)) * D + h * 64);
;         float qs = 0.f, ks = 0.f;
; #pragma unroll
;         for (int c = 0; c < 8; ++c) { const v4u w = qp[c], x = kp[c];
;             qs += (bflo(w.x) * bflo(w.x) + bfhi(w.x) * bfhi(w.x)) + (bflo(w.y) * bflo(w.y) + bfhi(w.y) * bfhi(w.y)) + (bflo(w.z) * bflo(w.z) + bfhi(w.z) * bfhi(w.z)) + (bflo(w.w) * bflo(w.w) + bfhi(w.w) * bfhi(w.w));
;             ks += (bflo(x.x) * bflo(x.x) + bfhi(x.x) * bfhi(x.x)) + (bflo(x.y) * bflo(x.y) + bfhi(x.y) * bfhi(x.y)) + (bflo(x.z) * bflo(x.z) + bfhi(x.z) * bfhi(x.z)) + (bflo(x.w) * bflo(x.w) + bfhi(x.w) * bfhi(x.w)); }
.LBB0_548:
	s_ashr_i32 s8, s19, 31
	s_lshr_b32 s8, s8, 25
	s_add_i32 s8, s19, s8
	s_and_b32 s9, s8, 0x3ffff80
	s_ashr_i32 s22, s8, 7
	s_sub_i32 s9, s19, s9
	v_lshl_or_b32 v0, s9, 6, v12
	s_lshl_b32 s9, s22, 10
	s_and_b32 s9, s9, 0xffffe000
	v_add_u32_e32 v0, s9, v0
	s_waitcnt lgkmcnt(0)
	v_ashrrev_i32_e32 v1, 31, v0
	v_lshlrev_b64 v[0:1], 11, v[0:1]
	v_lshl_add_u64 v[2:3], s[4:5], 0, v[0:1]
	s_and_b32 s12, s8, 0x380
	v_lshl_add_u64 v[14:15], v[2:3], 0, s[12:13]
	global_load_dwordx4 v[24:27], v[14:15], off offset:1024
	v_lshl_add_u64 v[0:1], s[10:11], 0, v[0:1]
	v_lshl_add_u64 v[16:17], v[0:1], 0, s[12:13]
	global_load_dwordx4 v[28:31], v[16:17], off offset:1024
	global_load_dwordx4 v[32:35], v[14:15], off offset:1040
	global_load_dwordx4 v[36:39], v[16:17], off offset:1040
	global_load_dwordx4 v[4:7], v[14:15], off offset:1072
	global_load_dwordx4 v[40:43], v[14:15], off offset:1056
	global_load_dwordx4 v[0:3], v[16:17], off offset:1072
	global_load_dwordx4 v[8:11], v[16:17], off offset:1056
	global_load_dwordx4 v[176:179], v[14:15], off offset:1104
	global_load_dwordx4 v[180:183], v[14:15], off offset:1088
	global_load_dwordx4 v[184:187], v[16:17], off offset:1104
	global_load_dwordx4 v[188:191], v[16:17], off offset:1088
	global_load_dwordx4 v[192:195], v[14:15], off offset:1136
	global_load_dwordx4 v[196:199], v[14:15], off offset:1120
	global_load_dwordx4 v[200:203], v[16:17], off offset:1136
	global_load_dwordx4 v[204:207], v[16:17], off offset:1120
	s_mov_b32 s98, 0x2000000
	s_mov_b32 s99, 0
	v_lshl_add_u64 v[208:209], v[14:15], 0, s[98:99]
	global_load_dword v210, v[208:209], off offset:1024
	v_lshl_add_u64 v[208:209], v[16:17], 0, s[98:99]
	global_load_dword v210, v[208:209], off offset:1024
	s_waitcnt vmcnt(0)
	v_lshlrev_b32_e32 v48, 16, v28
	v_and_b32_e32 v28, 0xffff0000, v28
	v_lshlrev_b32_e32 v49, 16, v29
	v_lshlrev_b32_e32 v44, 16, v24
	v_and_b32_e32 v24, 0xffff0000, v24
	v_lshlrev_b32_e32 v45, 16, v25
	v_and_b32_e32 v25, 0xffff0000, v25
	v_and_b32_e32 v29, 0xffff0000, v29
	v_lshlrev_b32_e32 v52, 16, v32
	v_and_b32_e32 v32, 0xffff0000, v32
	v_lshlrev_b32_e32 v53, 16, v33
	v_and_b32_e32 v33, 0xffff0000, v33
	v_lshlrev_b32_e32 v46, 16, v26
	v_and_b32_e32 v26, 0xffff0000, v26
	v_lshlrev_b32_e32 v54, 16, v34
	v_and_b32_e32 v34, 0xffff0000, v34
	v_mul_f32_e32 v24, v24, v24
	v_mul_f32_e32 v25, v25, v25
	v_mul_f32_e32 v28, v28, v28
	v_mul_f32_e32 v29, v29, v29
	v_mul_f32_e32 v32, v32, v32
	v_mul_f32_e32 v33, v33, v33
	v_lshlrev_b32_e32 v47, 16, v27
	v_and_b32_e32 v27, 0xffff0000, v27
	v_lshlrev_b32_e32 v55, 16, v35
	v_and_b32_e32 v35, 0xffff0000, v35
	v_mul_f32_e32 v26, v26, v26
	v_mul_f32_e32 v34, v34, v34
	v_fmac_f32_e32 v24, v44, v44
	v_fmac_f32_e32 v25, v45, v45
	v_fmac_f32_e32 v28, v48, v48
	v_fmac_f32_e32 v29, v49, v49
	v_fmac_f32_e32 v32, v52, v52
	v_fmac_f32_e32 v33, v53, v53
	v_mul_f32_e32 v27, v27, v27
	v_mul_f32_e32 v35, v35, v35
	v_fmac_f32_e32 v26, v46, v46
	v_fmac_f32_e32 v34, v54, v54
	v_add_f32_e32 v24, v24, v25
	v_add_f32_e32 v25, v28, v29
	v_add_f32_e32 v28, v32, v33
	v_lshlrev_b32_e32 v56, 16, v36
	v_and_b32_e32 v36, 0xffff0000, v36
	v_lshlrev_b32_e32 v57, 16, v37
	v_and_b32_e32 v37, 0xffff0000, v37
	v_fmac_f32_e32 v27, v47, v47
	v_fmac_f32_e32 v35, v55, v55
	v_add_f32_e32 v24, v26, v24
	v_add_f32_e32 v26, v34, v28
	v_lshlrev_b32_e32 v50, 16, v30
	v_and_b32_e32 v30, 0xffff0000, v30
	v_lshlrev_b32_e32 v58, 16, v38
	v_and_b32_e32 v38, 0xffff0000, v38
	v_mul_f32_e32 v36, v36, v36
	v_mul_f32_e32 v37, v37, v37
	v_add_f32_e32 v24, v27, v24
	v_add_f32_e32 v26, v35, v26
	v_lshlrev_b32_e32 v51, 16, v31
	v_and_b32_e32 v31, 0xffff0000, v31
	v_mul_f32_e32 v30, v30, v30
	v_mul_f32_e32 v38, v38, v38
	v_fmac_f32_e32 v36, v56, v56
	v_fmac_f32_e32 v37, v57, v57
	v_add_f32_e32 v32, v24, v26
	v_and_b32_e32 v24, 0xffff0000, v39
	v_lshlrev_b32_e32 v59, 16, v39
	v_mul_f32_e32 v31, v31, v31
	v_fmac_f32_e32 v30, v50, v50
	v_fmac_f32_e32 v38, v58, v58
	v_add_f32_e32 v29, v36, v37
	v_mul_f32_e32 v24, v24, v24
	v_fmac_f32_e32 v31, v51, v51
	v_add_f32_e32 v25, v30, v25
	v_add_f32_e32 v28, v38, v29
	v_fmac_f32_e32 v24, v59, v59
	v_add_f32_e32 v25, v31, v25
	v_add_f32_e32 v24, v24, v28
	v_add_f32_e32 v44, v25, v24
	v_and_b32_e32 v25, 0xffff0000, v40
	v_lshlrev_b32_e32 v24, 16, v40
	v_mul_f32_e32 v33, v25, v25
	v_fmac_f32_e32 v33, v24, v24
	v_and_b32_e32 v24, 0xffff0000, v41
	v_lshlrev_b32_e32 v34, 16, v41
	v_mul_f32_e32 v35, v24, v24
	v_mov_b32_e32 v24, v176
	v_mov_b32_e32 v25, v177
	v_mov_b32_e32 v26, v178
	v_mov_b32_e32 v27, v179
	v_mov_b32_e32 v28, v180
	v_mov_b32_e32 v29, v181
	v_mov_b32_e32 v30, v182
	v_mov_b32_e32 v31, v183
	v_fmac_f32_e32 v35, v34, v34
	v_add_f32_e32 v33, v33, v35
	v_and_b32_e32 v35, 0xffff0000, v42
	v_lshlrev_b32_e32 v34, 16, v42
	v_mul_f32_e32 v35, v35, v35
	v_fmac_f32_e32 v35, v34, v34
	v_add_f32_e32 v33, v35, v33
	v_and_b32_e32 v35, 0xffff0000, v43
	v_lshlrev_b32_e32 v34, 16, v43
	v_mul_f32_e32 v35, v35, v35
	v_fmac_f32_e32 v35, v34, v34
	v_add_f32_e32 v33, v35, v33
	v_add_f32_e32 v40, v32, v33
	v_lshlrev_b32_e32 v32, 16, v8
	v_and_b32_e32 v8, 0xffff0000, v8
	v_mul_f32_e32 v8, v8, v8
	v_lshlrev_b32_e32 v41, 16, v9
	v_and_b32_e32 v9, 0xffff0000, v9
	v_fmac_f32_e32 v8, v32, v32
	v_mov_b32_e32 v32, v184
	v_mov_b32_e32 v33, v185
	v_mov_b32_e32 v34, v186
	v_mov_b32_e32 v35, v187
	v_mov_b32_e32 v36, v188
	v_mov_b32_e32 v37, v189
	v_mov_b32_e32 v38, v190
	v_mov_b32_e32 v39, v191
	v_mul_f32_e32 v9, v9, v9
	v_fmac_f32_e32 v9, v41, v41
	v_add_f32_e32 v8, v8, v9
	v_lshlrev_b32_e32 v9, 16, v10
	v_and_b32_e32 v10, 0xffff0000, v10
	v_mul_f32_e32 v10, v10, v10
	v_fmac_f32_e32 v10, v9, v9
	v_add_f32_e32 v8, v10, v8
; __device__ __forceinline__ float bflo(unsigned w) { return __uint_as_float(w << 16); }
; __device__ __forceinline__ float bfhi(unsigned w) { return __uint_as_float(w & 0xffff0000u); }
; __device__ __forceinline__ void prep_phase(const Args& a, LAS unsigned char* lds, int tid, int lane, int wave) {
;     ...
;         for (int c = 0; c < 8; ++c) { const v4u w = qp[c], x = kp[c];
;             qs += (bflo(w.x) * bflo(w.x) + bfhi(w.x) * bfhi(w.x)) + (bflo(w.y) * bflo(w.y) + bfhi(w.y) * bfhi(w.y)) + (bflo(w.z) * bflo(w.z) + bfhi(w.z) * bfhi(w.z)) + (bflo(w.w) * bflo(w.w) + bfhi(w.w) * bfhi(w.w));
;             ks += (bflo(x.x) * bflo(x.x) + bfhi(x.x) * bfhi(x.x)) + (bflo(x.y) * bflo(x.y) + bfhi(x.y) * bfhi(x.y)) + (bflo(x.z) * bflo(x.z) + bfhi(x.z) * bfhi(x.z)) + (bflo(x.w) * bflo(x.w) + bfhi(x.w) * bfhi(x.w)); }
	v_and_b32_e32 v10, 0xffff0000, v11
	v_lshlrev_b32_e32 v9, 16, v11
	v_mul_f32_e32 v10, v10, v10
	v_fmac_f32_e32 v10, v9, v9
	v_lshlrev_b32_e32 v9, 16, v4
	v_and_b32_e32 v4, 0xffff0000, v4
	v_mul_f32_e32 v4, v4, v4
	v_fmac_f32_e32 v4, v9, v9
	v_lshlrev_b32_e32 v9, 16, v5
	v_and_b32_e32 v5, 0xffff0000, v5
	v_mul_f32_e32 v5, v5, v5
	v_fmac_f32_e32 v5, v9, v9
	v_add_f32_e32 v4, v4, v5
	v_lshlrev_b32_e32 v5, 16, v6
	v_and_b32_e32 v6, 0xffff0000, v6
	v_mul_f32_e32 v6, v6, v6
	v_fmac_f32_e32 v6, v5, v5
	v_add_f32_e32 v4, v6, v4
	v_and_b32_e32 v6, 0xffff0000, v7
	v_lshlrev_b32_e32 v5, 16, v7
	v_mul_f32_e32 v6, v6, v6
	v_fmac_f32_e32 v6, v5, v5
	v_add_f32_e32 v4, v6, v4
	v_add_f32_e32 v40, v40, v4
	v_lshlrev_b32_e32 v4, 16, v0
	v_and_b32_e32 v0, 0xffff0000, v0
	v_mul_f32_e32 v0, v0, v0
	v_fmac_f32_e32 v0, v4, v4
	v_lshlrev_b32_e32 v4, 16, v1
	v_and_b32_e32 v1, 0xffff0000, v1
	v_mul_f32_e32 v1, v1, v1
	v_fmac_f32_e32 v1, v4, v4
	v_add_f32_e32 v0, v0, v1
	v_lshlrev_b32_e32 v1, 16, v2
	v_and_b32_e32 v2, 0xffff0000, v2
	v_mul_f32_e32 v2, v2, v2
	v_fmac_f32_e32 v2, v1, v1
	v_add_f32_e32 v0, v2, v0
	v_and_b32_e32 v2, 0xffff0000, v3
	v_lshlrev_b32_e32 v1, 16, v3
	v_mul_f32_e32 v2, v2, v2
	v_add_f32_e32 v8, v10, v8
	v_fmac_f32_e32 v2, v1, v1
	v_add_f32_e32 v8, v44, v8
	v_add_f32_e32 v0, v2, v0
	v_add_f32_e32 v41, v8, v0
	v_mov_b32_e32 v0, v192
	v_mov_b32_e32 v1, v193
	v_mov_b32_e32 v2, v194
	v_mov_b32_e32 v3, v195
	v_mov_b32_e32 v4, v196
	v_mov_b32_e32 v5, v197
	v_mov_b32_e32 v6, v198
	v_mov_b32_e32 v7, v199
	v_mov_b32_e32 v8, v200
	v_mov_b32_e32 v9, v201
	v_mov_b32_e32 v10, v202
	v_mov_b32_e32 v11, v203
	s_nop 0
	v_mov_b32_e32 v14, v204
	v_mov_b32_e32 v15, v205
	v_mov_b32_e32 v16, v206
	v_mov_b32_e32 v17, v207
	s_waitcnt vmcnt(6)
	v_lshlrev_b32_e32 v42, 16, v28
	v_and_b32_e32 v28, 0xffff0000, v28
	v_mul_f32_e32 v28, v28, v28
	v_fmac_f32_e32 v28, v42, v42
	v_lshlrev_b32_e32 v42, 16, v29
	v_and_b32_e32 v29, 0xffff0000, v29
	v_mul_f32_e32 v29, v29, v29
	v_fmac_f32_e32 v29, v42, v42
	v_add_f32_e32 v28, v28, v29
	v_lshlrev_b32_e32 v29, 16, v30
	v_and_b32_e32 v30, 0xffff0000, v30
	v_mul_f32_e32 v30, v30, v30
	v_fmac_f32_e32 v30, v29, v29
	v_add_f32_e32 v28, v30, v28
	v_and_b32_e32 v30, 0xffff0000, v31
	v_lshlrev_b32_e32 v29, 16, v31
	v_mul_f32_e32 v30, v30, v30
	v_fmac_f32_e32 v30, v29, v29
	v_add_f32_e32 v28, v30, v28
	v_add_f32_e32 v28, v40, v28
	s_waitcnt vmcnt(4)
	v_and_b32_e32 v30, 0xffff0000, v36
	v_lshlrev_b32_e32 v29, 16, v36
	v_mul_f32_e32 v30, v30, v30
	v_and_b32_e32 v31, 0xffff0000, v37
	v_fmac_f32_e32 v30, v29, v29
	v_lshlrev_b32_e32 v29, 16, v37
	v_mul_f32_e32 v31, v31, v31
	v_fmac_f32_e32 v31, v29, v29
	v_add_f32_e32 v29, v30, v31
	v_and_b32_e32 v31, 0xffff0000, v38
	v_lshlrev_b32_e32 v30, 16, v38
	v_mul_f32_e32 v31, v31, v31
	v_fmac_f32_e32 v31, v30, v30
	v_add_f32_e32 v29, v31, v29
	v_and_b32_e32 v31, 0xffff0000, v39
	v_lshlrev_b32_e32 v30, 16, v39
	v_mul_f32_e32 v31, v31, v31
	v_fmac_f32_e32 v31, v30, v30
	v_lshlrev_b32_e32 v30, 16, v24
	v_and_b32_e32 v24, 0xffff0000, v24
	v_mul_f32_e32 v24, v24, v24
	v_fmac_f32_e32 v24, v30, v30
	v_lshlrev_b32_e32 v30, 16, v25
	v_and_b32_e32 v25, 0xffff0000, v25
	v_mul_f32_e32 v25, v25, v25
	v_fmac_f32_e32 v25, v30, v30
	v_add_f32_e32 v24, v24, v25
	v_lshlrev_b32_e32 v25, 16, v26
	v_and_b32_e32 v26, 0xffff0000, v26
	v_mul_f32_e32 v26, v26, v26
	v_fmac_f32_e32 v26, v25, v25
	v_add_f32_e32 v24, v26, v24
	v_and_b32_e32 v26, 0xffff0000, v27
	v_lshlrev_b32_e32 v25, 16, v27
	v_mul_f32_e32 v26, v26, v26
	v_fmac_f32_e32 v26, v25, v25
	v_add_f32_e32 v24, v26, v24
	v_and_b32_e32 v26, 0xffff0000, v32
	v_lshlrev_b32_e32 v25, 16, v32
	v_mul_f32_e32 v26, v26, v26
	v_and_b32_e32 v27, 0xffff0000, v33
	v_fmac_f32_e32 v26, v25, v25
	v_lshlrev_b32_e32 v25, 16, v33
	v_mul_f32_e32 v27, v27, v27
	v_fmac_f32_e32 v27, v25, v25
	v_add_f32_e32 v25, v26, v27
	v_and_b32_e32 v27, 0xffff0000, v34
	v_lshlrev_b32_e32 v26, 16, v34
	v_mul_f32_e32 v27, v27, v27
	v_fmac_f32_e32 v27, v26, v26
	v_add_f32_e32 v25, v27, v25
	v_and_b32_e32 v27, 0xffff0000, v35
	v_lshlrev_b32_e32 v26, 16, v35
	v_mul_f32_e32 v27, v27, v27
	v_fmac_f32_e32 v27, v26, v26
	s_waitcnt vmcnt(2)
; __device__ __forceinline__ float bflo(unsigned w) { return __uint_as_float(w << 16); }
; __device__ __forceinline__ float bfhi(unsigned w) { return __uint_as_float(w & 0xffff0000u); }
; __device__ __forceinline__ void prep_phase(const Args& a, LAS unsigned char* lds, int tid, int lane, int wave) {
;     ...
;         for (int c = 0; c < 8; ++c) { const v4u w = qp[c], x = kp[c];
;             qs += (bflo(w.x) * bflo(w.x) + bfhi(w.x) * bfhi(w.x)) + (bflo(w.y) * bflo(w.y) + bfhi(w.y) * bfhi(w.y)) + (bflo(w.z) * bflo(w.z) + bfhi(w.z) * bfhi(w.z)) + (bflo(w.w) * bflo(w.w) + bfhi(w.w) * bfhi(w.w));
;             ks += (bflo(x.x) * bflo(x.x) + bfhi(x.x) * bfhi(x.x)) + (bflo(x.y) * bflo(x.y) + bfhi(x.y) * bfhi(x.y)) + (bflo(x.z) * bflo(x.z) + bfhi(x.z) * bfhi(x.z)) + (bflo(x.w) * bflo(x.w) + bfhi(x.w) * bfhi(x.w)); }
; #pragma unroll
;         for (int o = 1; o < 64; o <<= 1) { qs = fmaxf(qs, __shfl_xor(qs, o)); ks = fmaxf(ks, __shfl_xor(ks, o)); }
;         if (lane == 0) { atomicMax((unsigned*)ws + 3700 + bh, __float_as_uint(qs)); atomicMax((unsigned*)ws + 3732 + bh, __float_as_uint(ks)); }
	v_lshlrev_b32_e32 v26, 16, v4
	v_and_b32_e32 v4, 0xffff0000, v4
	v_mul_f32_e32 v4, v4, v4
	v_fmac_f32_e32 v4, v26, v26
	v_lshlrev_b32_e32 v26, 16, v5
	v_and_b32_e32 v5, 0xffff0000, v5
	v_mul_f32_e32 v5, v5, v5
	v_fmac_f32_e32 v5, v26, v26
	v_add_f32_e32 v4, v4, v5
	v_lshlrev_b32_e32 v5, 16, v6
	v_and_b32_e32 v6, 0xffff0000, v6
	v_mul_f32_e32 v6, v6, v6
	v_fmac_f32_e32 v6, v5, v5
	v_add_f32_e32 v4, v6, v4
	v_and_b32_e32 v6, 0xffff0000, v7
	v_lshlrev_b32_e32 v5, 16, v7
	v_mul_f32_e32 v6, v6, v6
	v_fmac_f32_e32 v6, v5, v5
	v_add_f32_e32 v4, v6, v4
	s_waitcnt vmcnt(0)
	v_and_b32_e32 v6, 0xffff0000, v14
	v_lshlrev_b32_e32 v5, 16, v14
	v_mul_f32_e32 v6, v6, v6
	v_and_b32_e32 v7, 0xffff0000, v15
	v_fmac_f32_e32 v6, v5, v5
	v_lshlrev_b32_e32 v5, 16, v15
	v_mul_f32_e32 v7, v7, v7
	v_fmac_f32_e32 v7, v5, v5
	v_add_f32_e32 v5, v6, v7
	v_and_b32_e32 v7, 0xffff0000, v16
	v_lshlrev_b32_e32 v6, 16, v16
	v_mul_f32_e32 v7, v7, v7
	v_fmac_f32_e32 v7, v6, v6
	v_add_f32_e32 v5, v7, v5
	v_and_b32_e32 v7, 0xffff0000, v17
	v_lshlrev_b32_e32 v6, 16, v17
	v_mul_f32_e32 v7, v7, v7
	v_fmac_f32_e32 v7, v6, v6
	v_lshlrev_b32_e32 v6, 16, v0
	v_and_b32_e32 v0, 0xffff0000, v0
	v_mul_f32_e32 v0, v0, v0
	v_fmac_f32_e32 v0, v6, v6
	v_lshlrev_b32_e32 v6, 16, v1
	v_and_b32_e32 v1, 0xffff0000, v1
	v_mul_f32_e32 v1, v1, v1
	v_fmac_f32_e32 v1, v6, v6
	v_add_f32_e32 v0, v0, v1
	v_lshlrev_b32_e32 v1, 16, v2
	v_and_b32_e32 v2, 0xffff0000, v2
	v_mul_f32_e32 v2, v2, v2
	v_fmac_f32_e32 v2, v1, v1
	v_add_f32_e32 v0, v2, v0
	v_and_b32_e32 v2, 0xffff0000, v3
	v_lshlrev_b32_e32 v1, 16, v3
	v_mul_f32_e32 v2, v2, v2
	v_fmac_f32_e32 v2, v1, v1
	v_add_f32_e32 v0, v2, v0
	v_and_b32_e32 v2, 0xffff0000, v8
	v_lshlrev_b32_e32 v1, 16, v8
	v_mul_f32_e32 v2, v2, v2
	v_and_b32_e32 v3, 0xffff0000, v9
	v_fmac_f32_e32 v2, v1, v1
	v_lshlrev_b32_e32 v1, 16, v9
	v_mul_f32_e32 v3, v3, v3
	v_fmac_f32_e32 v3, v1, v1
	v_add_f32_e32 v1, v2, v3
	v_and_b32_e32 v3, 0xffff0000, v10
	v_lshlrev_b32_e32 v2, 16, v10
	v_mul_f32_e32 v3, v3, v3
	v_fmac_f32_e32 v3, v2, v2
	v_add_f32_e32 v29, v31, v29
	v_add_f32_e32 v1, v3, v1
	v_and_b32_e32 v3, 0xffff0000, v11
	v_add_f32_e32 v29, v41, v29
	v_add_f32_e32 v24, v28, v24
	v_add_f32_e32 v25, v27, v25
	v_lshlrev_b32_e32 v2, 16, v11
	v_mul_f32_e32 v3, v3, v3
	v_add_f32_e32 v25, v29, v25
	v_add_f32_e32 v4, v24, v4
	v_add_f32_e32 v5, v7, v5
	v_fmac_f32_e32 v3, v2, v2
	v_add_f32_e32 v5, v25, v5
	v_add_f32_e32 v0, v4, v0
	v_add_f32_e32 v1, v3, v1
	ds_bpermute_b32 v2, v13, v0
	v_add_f32_e32 v1, v5, v1
	ds_bpermute_b32 v3, v13, v1
	s_waitcnt lgkmcnt(1)
	v_max_f32_e32 v2, v2, v2
	v_max_f32_e32 v0, v0, v2
	s_waitcnt lgkmcnt(0)
	v_max_f32_e32 v2, v3, v3
	ds_bpermute_b32 v3, v18, v0
	v_max_f32_e32 v1, v1, v2
	ds_bpermute_b32 v2, v18, v1
	s_waitcnt lgkmcnt(1)
	v_max_f32_e32 v3, v3, v3
	v_max_f32_e32 v0, v0, v3
	s_waitcnt lgkmcnt(0)
	v_max_f32_e32 v2, v2, v2
	ds_bpermute_b32 v3, v19, v0
	v_max_f32_e32 v1, v1, v2
	ds_bpermute_b32 v2, v19, v1
	s_waitcnt lgkmcnt(1)
	v_max_f32_e32 v3, v3, v3
	v_max_f32_e32 v0, v0, v3
	s_waitcnt lgkmcnt(0)
	v_max_f32_e32 v2, v2, v2
	ds_bpermute_b32 v3, v20, v0
	v_max_f32_e32 v1, v1, v2
	ds_bpermute_b32 v2, v20, v1
	s_waitcnt lgkmcnt(1)
	v_max_f32_e32 v3, v3, v3
	v_max_f32_e32 v0, v0, v3
	s_waitcnt lgkmcnt(0)
	v_max_f32_e32 v2, v2, v2
	ds_bpermute_b32 v3, v21, v0
	v_max_f32_e32 v1, v1, v2
	ds_bpermute_b32 v4, v21, v1
	s_waitcnt lgkmcnt(1)
	v_max_f32_e32 v2, v3, v3
	v_max_f32_e32 v2, v0, v2
	s_waitcnt lgkmcnt(0)
	v_max_f32_e32 v0, v4, v4
	v_max_f32_e32 v0, v1, v0
	ds_bpermute_b32 v3, v22, v2
	ds_bpermute_b32 v1, v22, v0
	s_and_saveexec_b64 s[24:25], vcc
	s_cbranch_execz .LBB0_547
	s_waitcnt lgkmcnt(1)
	v_max_f32_e32 v3, v3, v3
	v_max_f32_e32 v2, v2, v2
	s_mov_b64 s[26:27], exec
	v_max_f32_e32 v2, v2, v3
	s_mov_b32 s12, 0
